# S5 scans: complex recurrence in 3 packed ops (one FMA with op_sel_hi + neg_lo instead of two half-used FMAs and a move), one bf16 pack per step with d16_hi store
# speedup vs baseline: 1.0120x; 1.0054x over previous
; __device__ __forceinline__ void s5_pass1(const Params& p, int layer, int task, char* sm) {
;     ...
;   for (int l = 0; l < 128; l++) S5_STEP(sU + l * 16)
;   *(float2*)(p.END + (((size_t)(b * 128 + c) * 32 + g) * 64 + lane) * 2) = make_float2(sr, si);
.Ls5scan_p1:
	v_add_u32_e32 v60, s2, v41
	s_waitcnt lgkmcnt(6)
	v_pk_mul_f32 v[124:125], v[12:13], v[42:43] op_sel:[0,1]
	v_pk_mul_f32 v[126:127], v[12:13], v[108:109] op_sel:[0,1]
	v_pk_mul_f32 v[134:135], v[34:35], v[36:37] op_sel:[0,1]
	v_pk_fma_f32 v[124:125], v[16:17], v[42:43], v[124:125] op_sel_hi:[1,0,1]
	v_pk_fma_f32 v[126:127], v[16:17], v[108:109], v[126:127] op_sel_hi:[1,0,1]
	v_pk_fma_f32 v[136:137], v[32:33], v[36:37], v[134:135] op_sel_hi:[1,0,1] neg_lo:[0,0,1]
	v_pk_fma_f32 v[124:125], v[18:19], v[44:45], v[124:125] op_sel_hi:[1,0,1]
	v_pk_fma_f32 v[126:127], v[18:19], v[110:111], v[126:127] op_sel_hi:[1,0,1]
	v_pk_add_f32 v[132:133], v[136:137], v[128:129]
	v_pk_fma_f32 v[124:125], v[14:15], v[44:45], v[124:125] op_sel:[0,1,0]
	v_pk_fma_f32 v[126:127], v[14:15], v[110:111], v[126:127] op_sel:[0,1,0]
	v_pk_mul_f32 v[134:135], v[34:35], v[132:133] op_sel:[0,1]
	ds_read_b128 v[42:45], v60 offset:256
	ds_read_b128 v[108:111], v60 offset:320
	s_waitcnt lgkmcnt(6)
	v_pk_fma_f32 v[124:125], v[20:21], v[46:47], v[124:125] op_sel_hi:[1,0,1]
	v_pk_fma_f32 v[126:127], v[20:21], v[112:113], v[126:127] op_sel_hi:[1,0,1]
	v_pk_fma_f32 v[136:137], v[32:33], v[132:133], v[134:135] op_sel_hi:[1,0,1] neg_lo:[0,0,1]
	v_pk_fma_f32 v[124:125], v[8:9], v[46:47], v[124:125] op_sel:[0,1,0]
	v_pk_fma_f32 v[126:127], v[8:9], v[112:113], v[126:127] op_sel:[0,1,0]
	v_pk_add_f32 v[36:37], v[136:137], v[130:131]
	v_pk_fma_f32 v[124:125], v[22:23], v[48:49], v[124:125] op_sel_hi:[1,0,1]
	v_pk_fma_f32 v[126:127], v[22:23], v[114:115], v[126:127] op_sel_hi:[1,0,1]
	v_pk_fma_f32 v[124:125], v[10:11], v[48:49], v[124:125] op_sel:[0,1,0]
	v_pk_fma_f32 v[126:127], v[10:11], v[114:115], v[126:127] op_sel:[0,1,0]
	ds_read_b128 v[46:49], v60 offset:272
	ds_read_b128 v[112:115], v60 offset:336
	s_waitcnt lgkmcnt(6)
	v_pk_fma_f32 v[124:125], v[24:25], v[50:51], v[124:125] op_sel_hi:[1,0,1]
	v_pk_fma_f32 v[126:127], v[24:25], v[116:117], v[126:127] op_sel_hi:[1,0,1]
	v_pk_fma_f32 v[124:125], v[4:5], v[50:51], v[124:125] op_sel:[0,1,0]
	v_pk_fma_f32 v[126:127], v[4:5], v[116:117], v[126:127] op_sel:[0,1,0]
	v_pk_fma_f32 v[124:125], v[26:27], v[52:53], v[124:125] op_sel_hi:[1,0,1]
	v_pk_fma_f32 v[126:127], v[26:27], v[118:119], v[126:127] op_sel_hi:[1,0,1]
	v_pk_fma_f32 v[124:125], v[6:7], v[52:53], v[124:125] op_sel:[0,1,0]
	v_pk_fma_f32 v[126:127], v[6:7], v[118:119], v[126:127] op_sel:[0,1,0]
	ds_read_b128 v[50:53], v60 offset:288
	ds_read_b128 v[116:119], v60 offset:352
	s_waitcnt lgkmcnt(6)
	v_pk_fma_f32 v[124:125], v[28:29], v[54:55], v[124:125] op_sel_hi:[1,0,1]
	v_pk_fma_f32 v[126:127], v[28:29], v[120:121], v[126:127] op_sel_hi:[1,0,1]
	v_pk_fma_f32 v[124:125], v[0:1], v[54:55], v[124:125] op_sel:[0,1,0]
	v_pk_fma_f32 v[126:127], v[0:1], v[120:121], v[126:127] op_sel:[0,1,0]
	v_pk_fma_f32 v[124:125], v[30:31], v[56:57], v[124:125] op_sel_hi:[1,0,1]
	v_pk_fma_f32 v[126:127], v[30:31], v[122:123], v[126:127] op_sel_hi:[1,0,1]
	v_pk_fma_f32 v[124:125], v[2:3], v[56:57], v[124:125] op_sel:[0,1,0]
	v_pk_fma_f32 v[126:127], v[2:3], v[122:123], v[126:127] op_sel:[0,1,0]
	ds_read_b128 v[54:57], v60 offset:304
	ds_read_b128 v[120:123], v60 offset:368
	s_addk_i32 s2, 0x80
	v_mov_b64_e32 v[128:129], v[124:125]
	v_mov_b64_e32 v[130:131], v[126:127]
	s_cmpk_eq_i32 s2, 0x1f80
	s_cbranch_scc0 .Ls5scan_p1
	v_pk_mul_f32 v[134:135], v[34:35], v[36:37] op_sel:[0,1]
	s_nop 0
	v_pk_fma_f32 v[136:137], v[32:33], v[36:37], v[134:135] op_sel_hi:[1,0,1] neg_lo:[0,0,1]
	s_nop 0
	v_pk_add_f32 v[132:133], v[136:137], v[128:129]
	s_nop 0
	v_pk_mul_f32 v[134:135], v[34:35], v[132:133] op_sel:[0,1]
	s_nop 0
	v_pk_fma_f32 v[136:137], v[32:33], v[132:133], v[134:135] op_sel_hi:[1,0,1] neg_lo:[0,0,1]
	s_nop 0
	v_pk_add_f32 v[36:37], v[136:137], v[130:131]
	s_nop 0
	s_waitcnt lgkmcnt(0)
	v_mov_b32_e32 v38, v37
	s_lshl_b32 s1, s1, 12
	s_lshl_b32 s0, s0, 5
	s_or_b32 s0, s0, s1
	v_or_b32_e32 v0, s0, v40
	v_lshlrev_b32_e32 v1, 1, v39
	v_readlane_b32 s0, v253, 38
	v_lshl_or_b32 v144, v0, 7, v1
	v_readlane_b32 s1, v253, 39
	v_readlane_b32 s2, v253, 40
	v_readlane_b32 s3, v253, 41
	v_lshl_add_u64 v[0:1], v[144:145], 2, s[0:1]
	v_readlane_b32 s4, v253, 42
	v_readlane_b32 s5, v253, 43
	v_readlane_b32 s6, v253, 44
	v_readlane_b32 s7, v253, 45
	global_store_dwordx2 v[0:1], v[36:37], off

; __device__ __forceinline__ float ozero() { float z = 0.f; asm volatile("" : "+v"(z)); return z; }
; __device__ __forceinline__ bf f2bf(float f) { return (bf)(pk2(f, 0.f) & 0xFFFFu); }
; __device__ __forceinline__ f32x4 mfma16(bf16x8 a, bf16x8 b, f32x4 c) { return __builtin_amdgcn_mfma_f32_16x16x32_bf16(a, b, c, 0, 0, 0); }
; __device__ __forceinline__ void s5_pass2(const Params& p, int layer, int task, char* sm) {
;     ...
;       for (int l = 0; l < 32; l++) {
;         S5_STEP(sU + l * 16)
;         sS[l * 136 + lane] = f2bf(sr); sS[l * 136 + 64 + lane] = f2bf(si);
;       }
;       __builtin_amdgcn_wave_barrier();
; #pragma unroll
;       for (int mb = 0; mb < 2; mb++) {
;         const float z_ = ozero(); f32x4 acc = {z_, z_, z_, z_};
; #pragma unroll
;         for (int ks = 0; ks < 4; ks++) {
;           bf16x8 af = *(const bf16x8*)(sS + (16 * mb + (lane & 15)) * 136 + ks * 32 + 8 * (lane >> 4));
;           acc = mfma16(af, cf[ks], acc);
;         }
; #pragma unroll
;         for (int r = 0; r < 4; r++) {
;           const int l = 16 * mb + 4 * (lane >> 4) + r;
;           float y = acc[r] + dsk * sU[l * 16 + (lane & 15)];
;           p.YG[(tok0 + sub * 32 + l) * 512 + g * 16 + (lane & 15)] = f2bf(geluf_(y));
.Ls5scan_0:
	v_add_u32_e32 v41, s9, v79
	v_add_u32_e32 v103, v79, v40
	s_waitcnt lgkmcnt(8)
	v_pk_mul_f32 v[136:137], v[20:21], v[104:105] op_sel:[0,1]
	v_pk_mul_f32 v[138:139], v[20:21], v[120:121] op_sel:[0,1]
	v_pk_mul_f32 v[76:77], v[74:75], v[70:71] op_sel:[0,1]
	v_pk_fma_f32 v[136:137], v[52:53], v[104:105], v[136:137] op_sel_hi:[1,0,1]
	v_pk_fma_f32 v[138:139], v[52:53], v[120:121], v[138:139] op_sel_hi:[1,0,1]
	v_pk_fma_f32 v[146:147], v[68:69], v[70:71], v[76:77] op_sel_hi:[1,0,1] neg_lo:[0,0,1]
	v_pk_fma_f32 v[136:137], v[54:55], v[106:107], v[136:137] op_sel_hi:[1,0,1]
	v_pk_fma_f32 v[138:139], v[54:55], v[122:123], v[138:139] op_sel_hi:[1,0,1]
	v_pk_add_f32 v[42:43], v[146:147], v[140:141]
	v_pk_fma_f32 v[136:137], v[22:23], v[106:107], v[136:137] op_sel:[0,1,0]
	v_pk_fma_f32 v[138:139], v[22:23], v[122:123], v[138:139] op_sel:[0,1,0]
	v_cvt_pk_bf16_f32 v150, v42, v43
	ds_write_b16 v103, v150
	ds_write_b16_d16_hi v103, v150 offset:128
	ds_read_b128 v[104:107], v41 offset:256
	ds_read_b128 v[120:123], v41 offset:320
	s_waitcnt lgkmcnt(8)
	v_pk_fma_f32 v[136:137], v[56:57], v[108:109], v[136:137] op_sel_hi:[1,0,1]
	v_pk_fma_f32 v[138:139], v[56:57], v[124:125], v[138:139] op_sel_hi:[1,0,1]
	v_pk_mul_f32 v[76:77], v[74:75], v[42:43] op_sel:[0,1]
	v_pk_fma_f32 v[136:137], v[16:17], v[108:109], v[136:137] op_sel:[0,1,0]
	v_pk_fma_f32 v[138:139], v[16:17], v[124:125], v[138:139] op_sel:[0,1,0]
	v_pk_fma_f32 v[146:147], v[68:69], v[42:43], v[76:77] op_sel_hi:[1,0,1] neg_lo:[0,0,1]
	v_pk_fma_f32 v[136:137], v[58:59], v[110:111], v[136:137] op_sel_hi:[1,0,1]
	v_pk_fma_f32 v[138:139], v[58:59], v[126:127], v[138:139] op_sel_hi:[1,0,1]
	v_pk_add_f32 v[70:71], v[146:147], v[142:143]
	v_pk_fma_f32 v[136:137], v[18:19], v[110:111], v[136:137] op_sel:[0,1,0]
	v_pk_fma_f32 v[138:139], v[18:19], v[126:127], v[138:139] op_sel:[0,1,0]
	v_cvt_pk_bf16_f32 v150, v70, v71
	ds_write_b16 v103, v150 offset:272
	ds_write_b16_d16_hi v103, v150 offset:400
	ds_read_b128 v[108:111], v41 offset:272
	ds_read_b128 v[124:127], v41 offset:336
	s_waitcnt lgkmcnt(10)
	v_pk_fma_f32 v[136:137], v[60:61], v[112:113], v[136:137] op_sel_hi:[1,0,1]
	v_pk_fma_f32 v[138:139], v[60:61], v[128:129], v[138:139] op_sel_hi:[1,0,1]
	v_pk_fma_f32 v[136:137], v[12:13], v[112:113], v[136:137] op_sel:[0,1,0]
	v_pk_fma_f32 v[138:139], v[12:13], v[128:129], v[138:139] op_sel:[0,1,0]
	v_pk_fma_f32 v[136:137], v[62:63], v[114:115], v[136:137] op_sel_hi:[1,0,1]
	v_pk_fma_f32 v[138:139], v[62:63], v[130:131], v[138:139] op_sel_hi:[1,0,1]
	v_pk_fma_f32 v[136:137], v[14:15], v[114:115], v[136:137] op_sel:[0,1,0]
	v_pk_fma_f32 v[138:139], v[14:15], v[130:131], v[138:139] op_sel:[0,1,0]
	ds_read_b128 v[112:115], v41 offset:288
	ds_read_b128 v[128:131], v41 offset:352
	s_waitcnt lgkmcnt(10)
	v_pk_fma_f32 v[136:137], v[64:65], v[116:117], v[136:137] op_sel_hi:[1,0,1]
	v_pk_fma_f32 v[138:139], v[64:65], v[132:133], v[138:139] op_sel_hi:[1,0,1]
	v_pk_fma_f32 v[136:137], v[8:9], v[116:117], v[136:137] op_sel:[0,1,0]
	v_pk_fma_f32 v[138:139], v[8:9], v[132:133], v[138:139] op_sel:[0,1,0]
	v_pk_fma_f32 v[136:137], v[66:67], v[118:119], v[136:137] op_sel_hi:[1,0,1]
	v_pk_fma_f32 v[138:139], v[66:67], v[134:135], v[138:139] op_sel_hi:[1,0,1]
	v_pk_fma_f32 v[136:137], v[10:11], v[118:119], v[136:137] op_sel:[0,1,0]
	v_pk_fma_f32 v[138:139], v[10:11], v[134:135], v[138:139] op_sel:[0,1,0]
	ds_read_b128 v[116:119], v41 offset:304
	ds_read_b128 v[132:135], v41 offset:368
	s_addk_i32 s9, 0x80
	v_add_u32_e32 v40, 0x220, v40
	v_mov_b64_e32 v[140:141], v[136:137]
	v_mov_b64_e32 v[142:143], v[138:139]
	s_cmpk_eq_i32 s9, 0x780
	s_cbranch_scc0 .Ls5scan_0
	v_add_u32_e32 v103, v79, v40
	v_pk_mul_f32 v[76:77], v[74:75], v[70:71] op_sel:[0,1]
	s_nop 0
	v_pk_fma_f32 v[146:147], v[68:69], v[70:71], v[76:77] op_sel_hi:[1,0,1] neg_lo:[0,0,1]
	s_nop 0
	v_pk_add_f32 v[42:43], v[146:147], v[140:141]
	s_nop 0
	v_cvt_pk_bf16_f32 v150, v42, v43
	s_nop 0
	ds_write_b16 v103, v150
	ds_write_b16_d16_hi v103, v150 offset:128
	v_pk_mul_f32 v[76:77], v[74:75], v[42:43] op_sel:[0,1]
	s_nop 0
	v_pk_fma_f32 v[146:147], v[68:69], v[42:43], v[76:77] op_sel_hi:[1,0,1] neg_lo:[0,0,1]
	s_nop 0
	v_pk_add_f32 v[70:71], v[146:147], v[142:143]
	s_nop 0
	v_cvt_pk_bf16_f32 v150, v70, v71
	s_nop 0
	ds_write_b16 v103, v150 offset:272
	ds_write_b16_d16_hi v103, v150 offset:400
	s_waitcnt lgkmcnt(0)
	v_mov_b32_e32 v40, v145
	ds_read_b128 v[104:107], v100 offset:2048
	ds_read_b32 v76, v83
	v_mov_b32_e32 v41, v40
	v_mov_b32_e32 v42, v40
	v_mov_b32_e32 v43, v40
	s_lshl_b32 s9, s11, 5
	v_mov_b32_e32 v77, s5
	s_cmp_eq_u32 s8, 4
	s_waitcnt vmcnt(4) lgkmcnt(1)
	v_mfma_f32_16x16x32_bf16 v[40:43], v[104:107], v[24:27], v[40:43]
	ds_read_b128 v[104:107], v100 offset:2112
	s_waitcnt vmcnt(3) lgkmcnt(0)
	v_mfma_f32_16x16x32_bf16 v[40:43], v[104:107], v[28:31], v[40:43]
	ds_read_b128 v[104:107], v100 offset:2176
	s_waitcnt vmcnt(2) lgkmcnt(0)
	v_mfma_f32_16x16x32_bf16 v[40:43], v[104:107], v[32:35], v[40:43]
	ds_read_b128 v[104:107], v100 offset:2240
	s_waitcnt vmcnt(1) lgkmcnt(0)
	v_mfma_f32_16x16x32_bf16 v[40:43], v[104:107], v[36:39], v[40:43]
	s_waitcnt vmcnt(0)
	s_nop 6
	v_fma_f32 v40, v102, v76, v40
	v_mul_f32_e32 v76, 0x3d372713, v40
	v_mul_f32_e32 v76, v40, v76
	v_fma_f32 v76, v40, v76, v40
	v_mul_f32_e32 v76, 0x3f4c422a, v76
	v_add_f32_e32 v76, v76, v76
	v_mul_f32_e32 v76, 0x3fb8aa3b, v76
	v_exp_f32_e32 v76, v76
	v_mul_f32_e32 v40, 0.5, v40
	v_add_f32_e32 v76, 1.0, v76
	v_rcp_f32_e32 v76, v76
	s_nop 0
	v_fma_f32 v76, v76, -2.0, 1.0
	v_add_f32_e32 v76, 1.0, v76
	v_mul_f32_e32 v40, v40, v76
	v_or_b32_e32 v76, s9, v82
	v_or_b32_e32 v76, s4, v76
	v_lshlrev_b64 v[104:105], 10, v[76:77]
	v_cvt_pk_bf16_f32 v40, v40, s0
	v_lshl_add_u64 v[104:105], v[72:73], 0, v[104:105]
	global_store_short v[104:105], v40, off
	ds_read_b32 v40, v85
	s_waitcnt lgkmcnt(0)
; __device__ __forceinline__ float ozero() { float z = 0.f; asm volatile("" : "+v"(z)); return z; }
; __device__ __forceinline__ bf f2bf(float f) { return (bf)(pk2(f, 0.f) & 0xFFFFu); }
; __device__ __forceinline__ f32x4 mfma16(bf16x8 a, bf16x8 b, f32x4 c) { return __builtin_amdgcn_mfma_f32_16x16x32_bf16(a, b, c, 0, 0, 0); }
; __device__ __forceinline__ void s5_pass2(const Params& p, int layer, int task, char* sm) {
;     ...
; #pragma unroll
;       for (int mb = 0; mb < 2; mb++) {
;         const float z_ = ozero(); f32x4 acc = {z_, z_, z_, z_};
; #pragma unroll
;         for (int ks = 0; ks < 4; ks++) {
;           bf16x8 af = *(const bf16x8*)(sS + (16 * mb + (lane & 15)) * 136 + ks * 32 + 8 * (lane >> 4));
;           acc = mfma16(af, cf[ks], acc);
;         }
; #pragma unroll
;         for (int r = 0; r < 4; r++) {
;           const int l = 16 * mb + 4 * (lane >> 4) + r;
;           float y = acc[r] + dsk * sU[l * 16 + (lane & 15)];
;           p.YG[(tok0 + sub * 32 + l) * 512 + g * 16 + (lane & 15)] = f2bf(geluf_(y));
;         }
;       }
	v_fma_f32 v40, v102, v40, v41
	v_mul_f32_e32 v41, 0x3d372713, v40
	v_mul_f32_e32 v41, v40, v41
	v_fma_f32 v41, v40, v41, v40
	v_mul_f32_e32 v41, 0x3f4c422a, v41
	v_add_f32_e32 v41, v41, v41
	v_mul_f32_e32 v41, 0x3fb8aa3b, v41
	v_exp_f32_e32 v41, v41
	v_mul_f32_e32 v40, 0.5, v40
	v_add_f32_e32 v41, 1.0, v41
	v_rcp_f32_e32 v41, v41
	s_nop 0
	v_fma_f32 v41, v41, -2.0, 1.0
	v_add_f32_e32 v41, 1.0, v41
	v_mul_f32_e32 v40, v40, v41
	v_cvt_pk_bf16_f32 v103, v40, s0
	v_or_b32_e32 v40, s9, v84
	v_or_b32_e32 v76, s4, v40
	v_lshlrev_b64 v[40:41], 10, v[76:77]
	v_lshl_add_u64 v[40:41], v[72:73], 0, v[40:41]
	global_store_short v[40:41], v103, off
	ds_read_b32 v40, v87
	s_waitcnt lgkmcnt(0)
	v_fma_f32 v40, v102, v40, v42
	v_mul_f32_e32 v41, 0x3d372713, v40
	v_mul_f32_e32 v41, v40, v41
	v_fma_f32 v41, v40, v41, v40
	v_mul_f32_e32 v41, 0x3f4c422a, v41
	v_add_f32_e32 v41, v41, v41
	v_mul_f32_e32 v41, 0x3fb8aa3b, v41
	v_exp_f32_e32 v41, v41
	v_mul_f32_e32 v40, 0.5, v40
	v_add_f32_e32 v41, 1.0, v41
	v_rcp_f32_e32 v41, v41
	s_nop 0
	v_fma_f32 v41, v41, -2.0, 1.0
	v_add_f32_e32 v41, 1.0, v41
	v_mul_f32_e32 v40, v40, v41
	v_cvt_pk_bf16_f32 v42, v40, s0
	v_or_b32_e32 v40, s9, v86
	v_or_b32_e32 v76, s4, v40
	v_lshlrev_b64 v[40:41], 10, v[76:77]
	v_lshl_add_u64 v[40:41], v[72:73], 0, v[40:41]
	global_store_short v[40:41], v42, off
	ds_read_b32 v40, v89
	s_waitcnt lgkmcnt(0)
	v_fmac_f32_e32 v43, v102, v40
	v_mul_f32_e32 v40, 0x3d372713, v43
	v_mul_f32_e32 v40, v43, v40
	v_fma_f32 v40, v43, v40, v43
	v_mul_f32_e32 v40, 0x3f4c422a, v40
	v_add_f32_e32 v40, v40, v40
	v_mul_f32_e32 v40, 0x3fb8aa3b, v40
	v_exp_f32_e32 v40, v40
	v_mul_f32_e32 v41, 0.5, v43
	v_add_f32_e32 v40, 1.0, v40
	v_rcp_f32_e32 v40, v40
	s_nop 0
	v_fma_f32 v40, v40, -2.0, 1.0
	v_add_f32_e32 v40, 1.0, v40
	v_mul_f32_e32 v40, v41, v40
	v_cvt_pk_bf16_f32 v42, v40, s0
	v_or_b32_e32 v40, s9, v88
	v_or_b32_e32 v76, s4, v40
	v_lshlrev_b64 v[40:41], 10, v[76:77]
	v_lshl_add_u64 v[40:41], v[72:73], 0, v[40:41]
	global_store_short v[40:41], v42, off
	v_mov_b32_e32 v40, v145
	ds_read_b128 v[104:107], v100 offset:6400
	ds_read_b32 v76, v91
	v_mov_b32_e32 v41, v40
	v_mov_b32_e32 v42, v40
	v_mov_b32_e32 v43, v40
	s_waitcnt lgkmcnt(1)
	s_nop 0
	v_mfma_f32_16x16x32_bf16 v[40:43], v[104:107], v[24:27], v[40:43]
	ds_read_b128 v[104:107], v100 offset:6464
	s_waitcnt lgkmcnt(0)
	v_mfma_f32_16x16x32_bf16 v[40:43], v[104:107], v[28:31], v[40:43]
	ds_read_b128 v[104:107], v100 offset:6528
	s_waitcnt lgkmcnt(0)
	v_mfma_f32_16x16x32_bf16 v[40:43], v[104:107], v[32:35], v[40:43]
	ds_read_b128 v[104:107], v100 offset:6592
	s_waitcnt lgkmcnt(0)
	v_mfma_f32_16x16x32_bf16 v[40:43], v[104:107], v[36:39], v[40:43]
	s_nop 7
	v_fma_f32 v40, v102, v76, v40
	v_mul_f32_e32 v76, 0x3d372713, v40
	v_mul_f32_e32 v76, v40, v76
	v_fma_f32 v76, v40, v76, v40
	v_mul_f32_e32 v76, 0x3f4c422a, v76
	v_add_f32_e32 v76, v76, v76
	v_mul_f32_e32 v76, 0x3fb8aa3b, v76
	v_exp_f32_e32 v76, v76
	v_mul_f32_e32 v40, 0.5, v40
	v_add_f32_e32 v76, 1.0, v76
	v_rcp_f32_e32 v76, v76
	s_nop 0
	v_fma_f32 v76, v76, -2.0, 1.0
	v_add_f32_e32 v76, 1.0, v76
	v_mul_f32_e32 v40, v40, v76
	v_or_b32_e32 v76, s9, v90
	v_or_b32_e32 v76, s4, v76
	v_lshlrev_b64 v[104:105], 10, v[76:77]
	v_cvt_pk_bf16_f32 v40, v40, s0
	v_lshl_add_u64 v[104:105], v[72:73], 0, v[104:105]
	global_store_short v[104:105], v40, off
	ds_read_b32 v40, v93
	s_waitcnt lgkmcnt(0)
	v_fma_f32 v40, v102, v40, v41
	v_mul_f32_e32 v41, 0x3d372713, v40
	v_mul_f32_e32 v41, v40, v41
	v_fma_f32 v41, v40, v41, v40
	v_mul_f32_e32 v41, 0x3f4c422a, v41
	v_add_f32_e32 v41, v41, v41
	v_mul_f32_e32 v41, 0x3fb8aa3b, v41
	v_exp_f32_e32 v41, v41
	v_mul_f32_e32 v40, 0.5, v40
	v_add_f32_e32 v41, 1.0, v41
	v_rcp_f32_e32 v41, v41
	s_nop 0
	v_fma_f32 v41, v41, -2.0, 1.0
	v_add_f32_e32 v41, 1.0, v41
	v_mul_f32_e32 v40, v40, v41
	v_cvt_pk_bf16_f32 v103, v40, s0
	v_or_b32_e32 v40, s9, v92
	v_or_b32_e32 v76, s4, v40
	v_lshlrev_b64 v[40:41], 10, v[76:77]
	v_lshl_add_u64 v[40:41], v[72:73], 0, v[40:41]
	global_store_short v[40:41], v103, off
	ds_read_b32 v40, v95
	s_waitcnt lgkmcnt(0)
	v_fma_f32 v40, v102, v40, v42
	v_mul_f32_e32 v41, 0x3d372713, v40
	v_mul_f32_e32 v41, v40, v41
	v_fma_f32 v41, v40, v41, v40
	v_mul_f32_e32 v41, 0x3f4c422a, v41
	v_add_f32_e32 v41, v41, v41
	v_mul_f32_e32 v41, 0x3fb8aa3b, v41
	v_exp_f32_e32 v41, v41
	v_mul_f32_e32 v40, 0.5, v40
	v_add_f32_e32 v41, 1.0, v41
	v_rcp_f32_e32 v41, v41
	s_nop 0
	v_fma_f32 v41, v41, -2.0, 1.0
	v_add_f32_e32 v41, 1.0, v41
	v_mul_f32_e32 v40, v40, v41
	v_cvt_pk_bf16_f32 v42, v40, s0
	v_or_b32_e32 v40, s9, v94
	v_or_b32_e32 v76, s4, v40
	v_lshlrev_b64 v[40:41], 10, v[76:77]
	v_lshl_add_u64 v[40:41], v[72:73], 0, v[40:41]
	global_store_short v[40:41], v42, off
	ds_read_b32 v40, v97
	s_waitcnt lgkmcnt(0)
	v_fmac_f32_e32 v43, v102, v40
	v_mul_f32_e32 v40, 0x3d372713, v43
	v_mul_f32_e32 v40, v43, v40
	v_fma_f32 v40, v43, v40, v43
	v_mul_f32_e32 v40, 0x3f4c422a, v40
	v_add_f32_e32 v40, v40, v40
	v_mul_f32_e32 v40, 0x3fb8aa3b, v40
	v_exp_f32_e32 v40, v40
	v_mul_f32_e32 v41, 0.5, v43
	v_add_f32_e32 v40, 1.0, v40
	v_rcp_f32_e32 v40, v40
	s_nop 0
	v_fma_f32 v40, v40, -2.0, 1.0
	v_add_f32_e32 v40, 1.0, v40
	v_mul_f32_e32 v40, v41, v40
	v_cvt_pk_bf16_f32 v42, v40, s0
	v_or_b32_e32 v40, s9, v96
	v_or_b32_e32 v76, s4, v40
	v_lshlrev_b64 v[40:41], 10, v[76:77]
	v_lshl_add_u64 v[40:41], v[72:73], 0, v[40:41]
	global_store_short v[40:41], v42, off
	s_cbranch_scc1 .LBB0_1789
	s_mov_b32 s11, s8
	s_branch .LBB0_1791

; __device__ __forceinline__ float ozero() { float z = 0.f; asm volatile("" : "+v"(z)); return z; }
; __device__ __forceinline__ bf f2bf(float f) { return (bf)(pk2(f, 0.f) & 0xFFFFu); }
; __device__ __forceinline__ f32x4 mfma16(bf16x8 a, bf16x8 b, f32x4 c) { return __builtin_amdgcn_mfma_f32_16x16x32_bf16(a, b, c, 0, 0, 0); }
; __device__ __forceinline__ void s5_pass2(const Params& p, int layer, int task, char* sm) {
;     ...
;       for (int l = 0; l < 32; l++) {
;         S5_STEP(sU + l * 16)
;         sS[l * 136 + lane] = f2bf(sr); sS[l * 136 + 64 + lane] = f2bf(si);
;       }
;       __builtin_amdgcn_wave_barrier();
; #pragma unroll
;       for (int mb = 0; mb < 2; mb++) {
;         const float z_ = ozero(); f32x4 acc = {z_, z_, z_, z_};
; #pragma unroll
;         for (int ks = 0; ks < 4; ks++) {
;           bf16x8 af = *(const bf16x8*)(sS + (16 * mb + (lane & 15)) * 136 + ks * 32 + 8 * (lane >> 4));
;           acc = mfma16(af, cf[ks], acc);
;         }
; #pragma unroll
;         for (int r = 0; r < 4; r++) {
;           const int l = 16 * mb + 4 * (lane >> 4) + r;
;           float y = acc[r] + dsk * sU[l * 16 + (lane & 15)];
;           p.YG[(tok0 + sub * 32 + l) * 512 + g * 16 + (lane & 15)] = f2bf(geluf_(y));
.Ls5scan_1:
	v_add_u32_e32 v41, s9, v79
	v_add_u32_e32 v103, v79, v40
	s_waitcnt lgkmcnt(8)
	v_pk_mul_f32 v[136:137], v[20:21], v[104:105] op_sel:[0,1]
	v_pk_mul_f32 v[138:139], v[20:21], v[120:121] op_sel:[0,1]
	v_pk_mul_f32 v[76:77], v[74:75], v[70:71] op_sel:[0,1]
	v_pk_fma_f32 v[136:137], v[52:53], v[104:105], v[136:137] op_sel_hi:[1,0,1]
	v_pk_fma_f32 v[138:139], v[52:53], v[120:121], v[138:139] op_sel_hi:[1,0,1]
	v_pk_fma_f32 v[146:147], v[68:69], v[70:71], v[76:77] op_sel_hi:[1,0,1] neg_lo:[0,0,1]
	v_pk_fma_f32 v[136:137], v[54:55], v[106:107], v[136:137] op_sel_hi:[1,0,1]
	v_pk_fma_f32 v[138:139], v[54:55], v[122:123], v[138:139] op_sel_hi:[1,0,1]
	v_pk_add_f32 v[42:43], v[146:147], v[140:141]
	v_pk_fma_f32 v[136:137], v[22:23], v[106:107], v[136:137] op_sel:[0,1,0]
	v_pk_fma_f32 v[138:139], v[22:23], v[122:123], v[138:139] op_sel:[0,1,0]
	v_cvt_pk_bf16_f32 v150, v42, v43
	ds_write_b16 v103, v150
	ds_write_b16_d16_hi v103, v150 offset:128
	ds_read_b128 v[104:107], v41 offset:256
	ds_read_b128 v[120:123], v41 offset:320
	s_waitcnt lgkmcnt(8)
	v_pk_fma_f32 v[136:137], v[56:57], v[108:109], v[136:137] op_sel_hi:[1,0,1]
	v_pk_fma_f32 v[138:139], v[56:57], v[124:125], v[138:139] op_sel_hi:[1,0,1]
	v_pk_mul_f32 v[76:77], v[74:75], v[42:43] op_sel:[0,1]
	v_pk_fma_f32 v[136:137], v[16:17], v[108:109], v[136:137] op_sel:[0,1,0]
	v_pk_fma_f32 v[138:139], v[16:17], v[124:125], v[138:139] op_sel:[0,1,0]
	v_pk_fma_f32 v[146:147], v[68:69], v[42:43], v[76:77] op_sel_hi:[1,0,1] neg_lo:[0,0,1]
	v_pk_fma_f32 v[136:137], v[58:59], v[110:111], v[136:137] op_sel_hi:[1,0,1]
	v_pk_fma_f32 v[138:139], v[58:59], v[126:127], v[138:139] op_sel_hi:[1,0,1]
	v_pk_add_f32 v[70:71], v[146:147], v[142:143]
	v_pk_fma_f32 v[136:137], v[18:19], v[110:111], v[136:137] op_sel:[0,1,0]
	v_pk_fma_f32 v[138:139], v[18:19], v[126:127], v[138:139] op_sel:[0,1,0]
	v_cvt_pk_bf16_f32 v150, v70, v71
	ds_write_b16 v103, v150 offset:272
	ds_write_b16_d16_hi v103, v150 offset:400
	ds_read_b128 v[108:111], v41 offset:272
	ds_read_b128 v[124:127], v41 offset:336
	s_waitcnt lgkmcnt(10)
	v_pk_fma_f32 v[136:137], v[60:61], v[112:113], v[136:137] op_sel_hi:[1,0,1]
	v_pk_fma_f32 v[138:139], v[60:61], v[128:129], v[138:139] op_sel_hi:[1,0,1]
	v_pk_fma_f32 v[136:137], v[12:13], v[112:113], v[136:137] op_sel:[0,1,0]
	v_pk_fma_f32 v[138:139], v[12:13], v[128:129], v[138:139] op_sel:[0,1,0]
	v_pk_fma_f32 v[136:137], v[62:63], v[114:115], v[136:137] op_sel_hi:[1,0,1]
	v_pk_fma_f32 v[138:139], v[62:63], v[130:131], v[138:139] op_sel_hi:[1,0,1]
	v_pk_fma_f32 v[136:137], v[14:15], v[114:115], v[136:137] op_sel:[0,1,0]
	v_pk_fma_f32 v[138:139], v[14:15], v[130:131], v[138:139] op_sel:[0,1,0]
	ds_read_b128 v[112:115], v41 offset:288
	ds_read_b128 v[128:131], v41 offset:352
	s_waitcnt lgkmcnt(10)
	v_pk_fma_f32 v[136:137], v[64:65], v[116:117], v[136:137] op_sel_hi:[1,0,1]
	v_pk_fma_f32 v[138:139], v[64:65], v[132:133], v[138:139] op_sel_hi:[1,0,1]
	v_pk_fma_f32 v[136:137], v[8:9], v[116:117], v[136:137] op_sel:[0,1,0]
	v_pk_fma_f32 v[138:139], v[8:9], v[132:133], v[138:139] op_sel:[0,1,0]
	v_pk_fma_f32 v[136:137], v[66:67], v[118:119], v[136:137] op_sel_hi:[1,0,1]
	v_pk_fma_f32 v[138:139], v[66:67], v[134:135], v[138:139] op_sel_hi:[1,0,1]
	v_pk_fma_f32 v[136:137], v[10:11], v[118:119], v[136:137] op_sel:[0,1,0]
	v_pk_fma_f32 v[138:139], v[10:11], v[134:135], v[138:139] op_sel:[0,1,0]
	ds_read_b128 v[116:119], v41 offset:304
	ds_read_b128 v[132:135], v41 offset:368
	s_addk_i32 s9, 0x80
	v_add_u32_e32 v40, 0x220, v40
	v_mov_b64_e32 v[140:141], v[136:137]
	v_mov_b64_e32 v[142:143], v[138:139]
	s_cmpk_eq_i32 s9, 0x780
	s_cbranch_scc0 .Ls5scan_1
	v_add_u32_e32 v103, v79, v40
	v_pk_mul_f32 v[76:77], v[74:75], v[70:71] op_sel:[0,1]
	s_nop 0
	v_pk_fma_f32 v[146:147], v[68:69], v[70:71], v[76:77] op_sel_hi:[1,0,1] neg_lo:[0,0,1]
	s_nop 0
	v_pk_add_f32 v[42:43], v[146:147], v[140:141]
	s_nop 0
	v_cvt_pk_bf16_f32 v150, v42, v43
	s_nop 0
	ds_write_b16 v103, v150
	ds_write_b16_d16_hi v103, v150 offset:128
	v_pk_mul_f32 v[76:77], v[74:75], v[42:43] op_sel:[0,1]
	s_nop 0
	v_pk_fma_f32 v[146:147], v[68:69], v[42:43], v[76:77] op_sel_hi:[1,0,1] neg_lo:[0,0,1]
	s_nop 0
	v_pk_add_f32 v[70:71], v[146:147], v[142:143]
	s_nop 0
	v_cvt_pk_bf16_f32 v150, v70, v71
	s_nop 0
	ds_write_b16 v103, v150 offset:272
	ds_write_b16_d16_hi v103, v150 offset:400
	s_waitcnt lgkmcnt(0)
	v_mov_b32_e32 v40, v145
	ds_read_b128 v[104:107], v100 offset:2048
	ds_read_b32 v76, v83
	v_mov_b32_e32 v41, v40
	v_mov_b32_e32 v42, v40
	v_mov_b32_e32 v43, v40
	s_lshl_b32 s9, s12, 5
	v_mov_b32_e32 v77, s5
	s_cmp_eq_u32 s8, 4
	s_waitcnt vmcnt(4) lgkmcnt(1)
	v_mfma_f32_16x16x32_bf16 v[40:43], v[104:107], v[24:27], v[40:43]
	ds_read_b128 v[104:107], v100 offset:2112
	s_waitcnt vmcnt(3) lgkmcnt(0)
	v_mfma_f32_16x16x32_bf16 v[40:43], v[104:107], v[28:31], v[40:43]
	ds_read_b128 v[104:107], v100 offset:2176
	s_waitcnt vmcnt(2) lgkmcnt(0)
	v_mfma_f32_16x16x32_bf16 v[40:43], v[104:107], v[32:35], v[40:43]
	ds_read_b128 v[104:107], v100 offset:2240
	s_waitcnt vmcnt(1) lgkmcnt(0)
	v_mfma_f32_16x16x32_bf16 v[40:43], v[104:107], v[36:39], v[40:43]
	s_waitcnt vmcnt(0)
	s_nop 6
	v_fma_f32 v40, v102, v76, v40
	v_mul_f32_e32 v76, 0x3d372713, v40
	v_mul_f32_e32 v76, v40, v76
	v_fma_f32 v76, v40, v76, v40
	v_mul_f32_e32 v76, 0x3f4c422a, v76
	v_add_f32_e32 v76, v76, v76
	v_mul_f32_e32 v76, 0x3fb8aa3b, v76
	v_exp_f32_e32 v76, v76
	v_mul_f32_e32 v40, 0.5, v40
	v_add_f32_e32 v76, 1.0, v76
	v_rcp_f32_e32 v76, v76
	s_nop 0
	v_fma_f32 v76, v76, -2.0, 1.0
	v_add_f32_e32 v76, 1.0, v76
	v_mul_f32_e32 v40, v40, v76
	v_or_b32_e32 v76, s9, v82
	v_or_b32_e32 v76, s4, v76
	v_lshlrev_b64 v[104:105], 10, v[76:77]
	v_cvt_pk_bf16_f32 v40, v40, s0
	v_lshl_add_u64 v[104:105], v[72:73], 0, v[104:105]
	global_store_short v[104:105], v40, off
	ds_read_b32 v40, v85
	s_waitcnt lgkmcnt(0)
; __device__ __forceinline__ float ozero() { float z = 0.f; asm volatile("" : "+v"(z)); return z; }
; __device__ __forceinline__ bf f2bf(float f) { return (bf)(pk2(f, 0.f) & 0xFFFFu); }
; __device__ __forceinline__ f32x4 mfma16(bf16x8 a, bf16x8 b, f32x4 c) { return __builtin_amdgcn_mfma_f32_16x16x32_bf16(a, b, c, 0, 0, 0); }
; __device__ __forceinline__ void s5_pass2(const Params& p, int layer, int task, char* sm) {
;     ...
; #pragma unroll
;       for (int mb = 0; mb < 2; mb++) {
;         const float z_ = ozero(); f32x4 acc = {z_, z_, z_, z_};
; #pragma unroll
;         for (int ks = 0; ks < 4; ks++) {
;           bf16x8 af = *(const bf16x8*)(sS + (16 * mb + (lane & 15)) * 136 + ks * 32 + 8 * (lane >> 4));
;           acc = mfma16(af, cf[ks], acc);
;         }
; #pragma unroll
;         for (int r = 0; r < 4; r++) {
;           const int l = 16 * mb + 4 * (lane >> 4) + r;
;           float y = acc[r] + dsk * sU[l * 16 + (lane & 15)];
;           p.YG[(tok0 + sub * 32 + l) * 512 + g * 16 + (lane & 15)] = f2bf(geluf_(y));
;         }
;       }
	v_fma_f32 v40, v102, v40, v41
	v_mul_f32_e32 v41, 0x3d372713, v40
	v_mul_f32_e32 v41, v40, v41
	v_fma_f32 v41, v40, v41, v40
	v_mul_f32_e32 v41, 0x3f4c422a, v41
	v_add_f32_e32 v41, v41, v41
	v_mul_f32_e32 v41, 0x3fb8aa3b, v41
	v_exp_f32_e32 v41, v41
	v_mul_f32_e32 v40, 0.5, v40
	v_add_f32_e32 v41, 1.0, v41
	v_rcp_f32_e32 v41, v41
	s_nop 0
	v_fma_f32 v41, v41, -2.0, 1.0
	v_add_f32_e32 v41, 1.0, v41
	v_mul_f32_e32 v40, v40, v41
	v_cvt_pk_bf16_f32 v103, v40, s0
	v_or_b32_e32 v40, s9, v84
	v_or_b32_e32 v76, s4, v40
	v_lshlrev_b64 v[40:41], 10, v[76:77]
	v_lshl_add_u64 v[40:41], v[72:73], 0, v[40:41]
	global_store_short v[40:41], v103, off
	ds_read_b32 v40, v87
	s_waitcnt lgkmcnt(0)
	v_fma_f32 v40, v102, v40, v42
	v_mul_f32_e32 v41, 0x3d372713, v40
	v_mul_f32_e32 v41, v40, v41
	v_fma_f32 v41, v40, v41, v40
	v_mul_f32_e32 v41, 0x3f4c422a, v41
	v_add_f32_e32 v41, v41, v41
	v_mul_f32_e32 v41, 0x3fb8aa3b, v41
	v_exp_f32_e32 v41, v41
	v_mul_f32_e32 v40, 0.5, v40
	v_add_f32_e32 v41, 1.0, v41
	v_rcp_f32_e32 v41, v41
	s_nop 0
	v_fma_f32 v41, v41, -2.0, 1.0
	v_add_f32_e32 v41, 1.0, v41
	v_mul_f32_e32 v40, v40, v41
	v_cvt_pk_bf16_f32 v42, v40, s0
	v_or_b32_e32 v40, s9, v86
	v_or_b32_e32 v76, s4, v40
	v_lshlrev_b64 v[40:41], 10, v[76:77]
	v_lshl_add_u64 v[40:41], v[72:73], 0, v[40:41]
	global_store_short v[40:41], v42, off
	ds_read_b32 v40, v89
	s_waitcnt lgkmcnt(0)
	v_fmac_f32_e32 v43, v102, v40
	v_mul_f32_e32 v40, 0x3d372713, v43
	v_mul_f32_e32 v40, v43, v40
	v_fma_f32 v40, v43, v40, v43
	v_mul_f32_e32 v40, 0x3f4c422a, v40
	v_add_f32_e32 v40, v40, v40
	v_mul_f32_e32 v40, 0x3fb8aa3b, v40
	v_exp_f32_e32 v40, v40
	v_mul_f32_e32 v41, 0.5, v43
	v_add_f32_e32 v40, 1.0, v40
	v_rcp_f32_e32 v40, v40
	s_nop 0
	v_fma_f32 v40, v40, -2.0, 1.0
	v_add_f32_e32 v40, 1.0, v40
	v_mul_f32_e32 v40, v41, v40
	v_cvt_pk_bf16_f32 v42, v40, s0
	v_or_b32_e32 v40, s9, v88
	v_or_b32_e32 v76, s4, v40
	v_lshlrev_b64 v[40:41], 10, v[76:77]
	v_lshl_add_u64 v[40:41], v[72:73], 0, v[40:41]
	global_store_short v[40:41], v42, off
	v_mov_b32_e32 v40, v145
	ds_read_b128 v[104:107], v100 offset:6400
	ds_read_b32 v76, v91
	v_mov_b32_e32 v41, v40
	v_mov_b32_e32 v42, v40
	v_mov_b32_e32 v43, v40
	s_waitcnt lgkmcnt(1)
	s_nop 0
	v_mfma_f32_16x16x32_bf16 v[40:43], v[104:107], v[24:27], v[40:43]
	ds_read_b128 v[104:107], v100 offset:6464
	s_waitcnt lgkmcnt(0)
	v_mfma_f32_16x16x32_bf16 v[40:43], v[104:107], v[28:31], v[40:43]
	ds_read_b128 v[104:107], v100 offset:6528
	s_waitcnt lgkmcnt(0)
	v_mfma_f32_16x16x32_bf16 v[40:43], v[104:107], v[32:35], v[40:43]
	ds_read_b128 v[104:107], v100 offset:6592
	s_waitcnt lgkmcnt(0)
	v_mfma_f32_16x16x32_bf16 v[40:43], v[104:107], v[36:39], v[40:43]
	s_nop 7
	v_fma_f32 v40, v102, v76, v40
	v_mul_f32_e32 v76, 0x3d372713, v40
	v_mul_f32_e32 v76, v40, v76
	v_fma_f32 v76, v40, v76, v40
	v_mul_f32_e32 v76, 0x3f4c422a, v76
	v_add_f32_e32 v76, v76, v76
	v_mul_f32_e32 v76, 0x3fb8aa3b, v76
	v_exp_f32_e32 v76, v76
	v_mul_f32_e32 v40, 0.5, v40
	v_add_f32_e32 v76, 1.0, v76
	v_rcp_f32_e32 v76, v76
	s_nop 0
	v_fma_f32 v76, v76, -2.0, 1.0
	v_add_f32_e32 v76, 1.0, v76
	v_mul_f32_e32 v40, v40, v76
	v_or_b32_e32 v76, s9, v90
	v_or_b32_e32 v76, s4, v76
	v_lshlrev_b64 v[104:105], 10, v[76:77]
	v_cvt_pk_bf16_f32 v40, v40, s0
	v_lshl_add_u64 v[104:105], v[72:73], 0, v[104:105]
	global_store_short v[104:105], v40, off
	ds_read_b32 v40, v93
	s_waitcnt lgkmcnt(0)
	v_fma_f32 v40, v102, v40, v41
	v_mul_f32_e32 v41, 0x3d372713, v40
	v_mul_f32_e32 v41, v40, v41
	v_fma_f32 v41, v40, v41, v40
	v_mul_f32_e32 v41, 0x3f4c422a, v41
	v_add_f32_e32 v41, v41, v41
	v_mul_f32_e32 v41, 0x3fb8aa3b, v41
	v_exp_f32_e32 v41, v41
	v_mul_f32_e32 v40, 0.5, v40
	v_add_f32_e32 v41, 1.0, v41
	v_rcp_f32_e32 v41, v41
	s_nop 0
	v_fma_f32 v41, v41, -2.0, 1.0
	v_add_f32_e32 v41, 1.0, v41
	v_mul_f32_e32 v40, v40, v41
	v_cvt_pk_bf16_f32 v103, v40, s0
	v_or_b32_e32 v40, s9, v92
	v_or_b32_e32 v76, s4, v40
	v_lshlrev_b64 v[40:41], 10, v[76:77]
	v_lshl_add_u64 v[40:41], v[72:73], 0, v[40:41]
	global_store_short v[40:41], v103, off
	ds_read_b32 v40, v95
	s_waitcnt lgkmcnt(0)
	v_fma_f32 v40, v102, v40, v42
	v_mul_f32_e32 v41, 0x3d372713, v40
	v_mul_f32_e32 v41, v40, v41
	v_fma_f32 v41, v40, v41, v40
	v_mul_f32_e32 v41, 0x3f4c422a, v41
	v_add_f32_e32 v41, v41, v41
	v_mul_f32_e32 v41, 0x3fb8aa3b, v41
	v_exp_f32_e32 v41, v41
	v_mul_f32_e32 v40, 0.5, v40
	v_add_f32_e32 v41, 1.0, v41
	v_rcp_f32_e32 v41, v41
	s_nop 0
	v_fma_f32 v41, v41, -2.0, 1.0
	v_add_f32_e32 v41, 1.0, v41
	v_mul_f32_e32 v40, v40, v41
	v_cvt_pk_bf16_f32 v42, v40, s0
	v_or_b32_e32 v40, s9, v94
	v_or_b32_e32 v76, s4, v40
	v_lshlrev_b64 v[40:41], 10, v[76:77]
	v_lshl_add_u64 v[40:41], v[72:73], 0, v[40:41]
	global_store_short v[40:41], v42, off
	ds_read_b32 v40, v97
	s_waitcnt lgkmcnt(0)
	v_fmac_f32_e32 v43, v102, v40
	v_mul_f32_e32 v40, 0x3d372713, v43
	v_mul_f32_e32 v40, v43, v40
	v_fma_f32 v40, v43, v40, v43
	v_mul_f32_e32 v40, 0x3f4c422a, v40
	v_add_f32_e32 v40, v40, v40
	v_mul_f32_e32 v40, 0x3fb8aa3b, v40
	v_exp_f32_e32 v40, v40
	v_mul_f32_e32 v41, 0.5, v43
	v_add_f32_e32 v40, 1.0, v40
	v_rcp_f32_e32 v40, v40
	s_nop 0
	v_fma_f32 v40, v40, -2.0, 1.0
	v_add_f32_e32 v40, 1.0, v40
	v_mul_f32_e32 v40, v41, v40
	v_cvt_pk_bf16_f32 v42, v40, s0
	v_or_b32_e32 v40, s9, v96
	v_or_b32_e32 v76, s4, v40
	v_lshlrev_b64 v[40:41], 10, v[76:77]
	v_lshl_add_u64 v[40:41], v[72:73], 0, v[40:41]
	global_store_short v[40:41], v42, off
	s_cbranch_scc1 .LBB0_2053
	s_mov_b32 s12, s8
	s_branch .LBB0_2055
